# ffn_up conv epilogue: interior-row fast path (no boundary masks, fused pk_fma chains, all LDS reads issued first)
# speedup vs baseline: 1.0196x; 1.0035x over previous
; static __device__ __forceinline__ void phase_ffn_up(const P& p, int l, char* lds) {
;     ...
; #pragma unroll
;     for (int tm = 0; tm < 4; ++tm) {
;       char* trow = tile + (wm * 64 + 16 * tm + (lane & 15)) * 528 + (wn * 64 + 4 * (lane >> 4)) * 4;
; #pragma unroll
;       for (int tn = 0; tn < 4; ++tn) *(f32x4*)(trow + 64 * tn) = acc[tm][tn];
;     }
;     __syncthreads();
;     {
;       const int cgp = tid & 7, wn2 = cgp >> 2, j0 = (cgp & 3) * 8;
;       const int ca0 = nt * 64 + wn2 * 32 + j0;
;       const int lca = (wn2 * 64 + j0) * 4, lcg = lca + 128;
;       float wa0[8], wa1[8], wa2[8], ba[8], wg0[8], wg1[8], wg2[8], bg[8];
; #pragma unroll
;       for (int e = 0; e < 8; ++e) {
;         wa0[e] = cw[ca0 + e]; wa1[e] = cw[5632 + ca0 + e]; wa2[e] = cw[2 * 5632 + ca0 + e]; ba[e] = cb[ca0 + e];
;         wg0[e] = cw[DFF + ca0 + e]; wg1[e] = cw[5632 + DFF + ca0 + e]; wg2[e] = cw[2 * 5632 + DFF + ca0 + e]; bg[e] = cb[DFF + ca0 + e];
;       }
; #pragma unroll
;       for (int jj = 0; jj < 4; ++jj) {
;         const int r = (tid >> 3) + 64 * jj, tt = tstart + r;
;         if (r >= 1 && r <= 254 && tt < MEND) {
;           const int pos = tt < MLAT ? (tt & (TLAT - 1)) : ((tt - MLAT) & (TCTX - 1)), slen = tt < MLAT ? TLAT : TCTX;
;           const float fm = pos == 0 ? 0.f : 1.f, fp = pos == slen - 1 ? 0.f : 1.f;
.LBB0_1077:
	v_lshl_or_b32 v114, s35, 6, v152
	v_ashrrev_i32_e32 v115, 31, v114
	ds_write_b128 v155, v[50:53] offset:2304
	ds_write_b128 v155, v[54:57] offset:2368
	ds_write_b128 v155, v[58:61] offset:2432
	ds_write_b128 v155, v[62:65] offset:2496
	ds_write_b128 v155, v[66:69] offset:10752
	ds_write_b128 v155, v[70:73] offset:10816
	ds_write_b128 v155, v[74:77] offset:10880
	ds_write_b128 v155, v[78:81] offset:10944
	ds_write_b128 v155, v[82:85] offset:19200
	ds_write_b128 v155, v[86:89] offset:19264
	ds_write_b128 v155, v[90:93] offset:19328
	ds_write_b128 v155, v[94:97] offset:19392
	ds_write_b128 v155, v[102:105] offset:27648
	ds_write_b128 v155, v[98:101] offset:27712
	ds_write_b128 v155, v[106:109] offset:27776
	ds_write_b128 v155, v[110:113] offset:27840
	v_lshlrev_b64 v[50:51], 2, v[114:115]
	v_lshl_add_u64 v[74:75], s[12:13], 0, v[50:51]
	s_mov_b64 s[20:21], 0x5800
	v_lshl_add_u64 v[54:55], v[74:75], 0, s[20:21]
	s_mov_b64 s[20:21], 0xb000
	v_lshl_add_u64 v[56:57], v[74:75], 0, s[20:21]
	s_mov_b64 s[20:21], 0x8400
	v_lshl_add_u64 v[70:71], v[74:75], 0, s[20:21]
	s_mov_b64 s[20:21], 0xdc00
	v_lshl_add_u64 v[76:77], v[74:75], 0, s[20:21]
	s_movk_i32 s20, 0x5000
	v_lshl_add_u64 v[78:79], s[16:17], 0, v[50:51]
	s_mov_b64 s[14:15], 0x2c00
	v_add_co_u32_e32 v58, vcc, s20, v74
	v_lshl_add_u64 v[66:67], v[74:75], 0, s[14:15]
	v_lshl_add_u64 v[80:81], v[78:79], 0, s[14:15]
	v_addc_co_u32_e32 v59, vcc, 0, v75, vcc
	s_mov_b32 s14, 0xb000
	v_add_co_u32_e32 v60, vcc, s14, v74
	s_movk_i32 s15, 0x2000
	s_nop 0
	v_addc_co_u32_e32 v61, vcc, 0, v75, vcc
	v_add_co_u32_e32 v68, vcc, s15, v74
	s_mov_b32 s14, 0x8000
	s_nop 0
	v_addc_co_u32_e32 v69, vcc, 0, v75, vcc
	v_add_co_u32_e32 v72, vcc, s14, v74
	s_mov_b32 s20, 0xd000
	s_nop 0
	v_addc_co_u32_e32 v73, vcc, 0, v75, vcc
	s_waitcnt lgkmcnt(0)
	global_load_dwordx4 v[50:53], v[74:75], off offset:16
	global_load_dwordx4 v[86:89], v[74:75], off
	global_load_dwordx4 v[94:97], v[58:59], off offset:2048
	global_load_dwordx4 v[90:93], v[60:61], off
	s_nop 0
	global_load_dwordx4 v[58:61], v[54:55], off offset:16
	s_nop 0
	global_load_dwordx4 v[54:57], v[56:57], off offset:16
	s_nop 0
	global_load_dwordx4 v[62:65], v[78:79], off offset:16
	global_load_dwordx4 v[82:85], v[78:79], off
	v_add_co_u32_e32 v74, vcc, s20, v74
	global_load_dwordx4 v[98:101], v[68:69], off offset:3072
	global_load_dwordx4 v[102:105], v[72:73], off offset:1024
	s_nop 0
	global_load_dwordx4 v[66:69], v[66:67], off offset:16
	s_nop 0
	global_load_dwordx4 v[70:73], v[70:71], off offset:16
	v_addc_co_u32_e32 v75, vcc, 0, v75, vcc
	v_add_co_u32_e32 v78, vcc, s15, v78
	global_load_dwordx4 v[106:109], v[74:75], off offset:3072
	s_nop 0
	global_load_dwordx4 v[74:77], v[76:77], off offset:16
	v_addc_co_u32_e32 v79, vcc, 0, v79, vcc
	global_load_dwordx4 v[110:113], v[78:79], off offset:3072
	s_nop 0
	global_load_dwordx4 v[78:81], v[80:81], off offset:16
	s_barrier
	s_mulk_i32 s34, 0xfe
	v_readlane_b32 s14, v254, 51
	v_add_u32_e32 v158, s34, v140
	v_readlane_b32 s15, v254, 52
	v_cmp_gt_i32_e32 vcc, s24, v158
	s_movk_i32 s81, 0x2000
	v_lshl_add_u64 v[132:133], v[114:115], 1, s[14:15]
	s_and_b64 s[22:23], s[4:5], vcc
	s_waitcnt vmcnt(0)
	s_and_saveexec_b64 s[20:21], s[22:23]
	s_cbranch_execz .LBB0_1079
	v_add_u32_e32 v159, v151, v150
	v_cmp_gt_i32_e32 vcc, s39, v158
	s_nop 1
	v_cndmask_b32_e32 v114, v235, v236, vcc
	v_and_b32_e32 v115, v114, v158
	v_cmp_eq_u32_e64 s[100:101], 0, v115
	v_cmp_eq_u32_e32 vcc, v115, v114
	s_nop 3
	s_or_b64 s[100:101], s[100:101], vcc
	s_cbranch_scc0 .Lcf_0
	v_add_u32_e32 v159, v151, v150
	v_cmp_gt_i32_e32 vcc, s39, v158
	ds_read_b128 v[136:139], v159 offset:1904
	ds_read_b128 v[160:163], v159 offset:2432
	v_cndmask_b32_e32 v114, v235, v236, vcc
	v_and_b32_e32 v115, v114, v158
	ds_read_b128 v[164:167], v159 offset:2960
	ds_read_b128 v[168:171], v159 offset:1776
	v_cmp_eq_u32_e32 vcc, 0, v115
	s_waitcnt vmcnt(6) lgkmcnt(2)
	v_pk_mul_f32 v[116:117], v[102:103], v[160:161]
	v_pk_mul_f32 v[162:163], v[104:105], v[162:163]
	v_cndmask_b32_e64 v0, 1.0, 0, vcc
	v_cmp_eq_u32_e32 vcc, v115, v114
	v_pk_mul_f32 v[114:115], v[0:1], v[136:137] op_sel_hi:[0,1]
	v_pk_fma_f32 v[114:115], v[98:99], v[114:115], v[116:117]
	v_cndmask_b32_e64 v134, 1.0, 0, vcc
	s_waitcnt lgkmcnt(1)
	v_pk_mul_f32 v[116:117], v[134:135], v[164:165] op_sel_hi:[0,1]
	s_waitcnt vmcnt(3)
	v_pk_fma_f32 v[114:115], v[106:107], v[116:117], v[114:115]
	v_pk_mul_f32 v[138:139], v[0:1], v[138:139] op_sel_hi:[0,1]
	s_waitcnt vmcnt(1)
	v_pk_add_f32 v[136:137], v[110:111], v[114:115]
	v_pk_fma_f32 v[138:139], v[100:101], v[138:139], v[162:163]
	v_mul_f32_e32 v114, 0xbfb8aa3b, v136
	v_mul_f32_e32 v161, 0xbfb8aa3b, v137
	v_exp_f32_e32 v160, v114
	ds_read_b128 v[114:117], v159 offset:1792
	ds_read_b128 v[172:175], v159 offset:2304
	ds_read_b128 v[176:179], v159 offset:2832
	v_exp_f32_e32 v161, v161
	v_pk_mul_f32 v[162:163], v[134:135], v[166:167] op_sel_hi:[0,1]
	v_pk_fma_f32 v[138:139], v[108:109], v[162:163], v[138:139]
	v_add_f32_e32 v160, 1.0, v160
	v_pk_add_f32 v[138:139], v[112:113], v[138:139]
	s_waitcnt lgkmcnt(3)
	v_pk_mul_f32 v[164:165], v[0:1], v[168:169] op_sel_hi:[0,1]
	s_waitcnt lgkmcnt(1)
	v_pk_mul_f32 v[168:169], v[94:95], v[172:173]
	v_add_f32_e32 v161, 1.0, v161
	v_mul_f32_e32 v162, 0xbfb8aa3b, v138
	v_rcp_f32_e32 v160, v160
	v_pk_fma_f32 v[164:165], v[86:87], v[164:165], v[168:169]
	s_waitcnt lgkmcnt(0)
; DI unsigned pk2(float a, float b) { f32x2 v = {a, b}; bf16x2_t r = __builtin_convertvector(v, bf16x2_t); return __builtin_bit_cast(unsigned, r); }
; DI float silu_f(float g) { return g * rcpf_(1.f + ex2(-g * LOG2E)); }
; static __device__ __forceinline__ void phase_ffn_up(const P& p, int l, char* lds) {
;     ...
; #pragma unroll
;       for (int jj = 0; jj < 4; ++jj) {
;         const int r = (tid >> 3) + 64 * jj, tt = tstart + r;
;         if (r >= 1 && r <= 254 && tt < MEND) {
;           const int pos = tt < MLAT ? (tt & (TLAT - 1)) : ((tt - MLAT) & (TCTX - 1)), slen = tt < MLAT ? TLAT : TCTX;
;           const float fm = pos == 0 ? 0.f : 1.f, fp = pos == slen - 1 ? 0.f : 1.f;
;           const char* rp = tile + r * 528;
;           float o[8];
; #pragma unroll
;           for (int hf = 0; hf < 2; ++hf) {
;             const f32x4 am = *(const f32x4*)(rp - 528 + lca + hf * 16), a0 = *(const f32x4*)(rp + lca + hf * 16), ap = *(const f32x4*)(rp + 528 + lca + hf * 16);
;             const f32x4 gm = *(const f32x4*)(rp - 528 + lcg + hf * 16), g0 = *(const f32x4*)(rp + lcg + hf * 16), gp = *(const f32x4*)(rp + 528 + lcg + hf * 16);
; #pragma unroll
;             for (int e = 0; e < 4; ++e) {
;               const int q = hf * 4 + e;
;               const float ua = wa0[q] * (fm * am[e]) + wa1[q] * a0[e] + wa2[q] * (fp * ap[e]) + ba[q];
;               const float ug = wg0[q] * (fm * gm[e]) + wg1[q] * g0[e] + wg2[q] * (fp * gp[e]) + bg[q];
;               o[q] = silu_f(ug) * ua;
;             }
;           }
;           u32x4 w = {pk2(o[0], o[1]), pk2(o[2], o[3]), pk2(o[4], o[5]), pk2(o[6], o[7])};
;           *(u32x4*)(act + (size_t)tt * DFF + ca0) = w;
	v_pk_mul_f32 v[168:169], v[134:135], v[176:177] op_sel_hi:[0,1]
	v_rcp_f32_e32 v161, v161
	v_exp_f32_e32 v166, v162
	v_pk_fma_f32 v[164:165], v[90:91], v[168:169], v[164:165]
	v_pk_mul_f32 v[114:115], v[0:1], v[114:115] op_sel_hi:[0,1]
	v_pk_add_f32 v[162:163], v[82:83], v[164:165]
	v_mul_f32_e32 v164, 0xbfb8aa3b, v139
	v_exp_f32_e32 v164, v164
	v_pk_mul_f32 v[136:137], v[136:137], v[160:161]
	v_add_f32_e32 v160, 1.0, v166
	v_pk_mul_f32 v[136:137], v[162:163], v[136:137]
	v_rcp_f32_e32 v172, v160
	v_pk_mul_f32 v[160:161], v[0:1], v[170:171] op_sel_hi:[0,1]
	v_pk_mul_f32 v[162:163], v[96:97], v[174:175]
	v_pk_mul_f32 v[116:117], v[0:1], v[116:117] op_sel_hi:[0,1]
	v_pk_fma_f32 v[160:161], v[88:89], v[160:161], v[162:163]
	v_pk_mul_f32 v[162:163], v[134:135], v[178:179] op_sel_hi:[0,1]
	v_pk_fma_f32 v[168:169], v[92:93], v[162:163], v[160:161]
	v_add_f32_e32 v160, 1.0, v164
	v_rcp_f32_e32 v173, v160
	ds_read_b128 v[160:163], v159 offset:1920
	ds_read_b128 v[164:167], v159 offset:2448
	v_pk_add_f32 v[174:175], v[84:85], v[168:169]
	ds_read_b128 v[168:171], v159 offset:2976
	v_pk_mul_f32 v[138:139], v[138:139], v[172:173]
	s_waitcnt lgkmcnt(2)
	v_pk_mul_f32 v[160:161], v[0:1], v[160:161] op_sel_hi:[0,1]
	s_waitcnt lgkmcnt(1)
	v_pk_mul_f32 v[164:165], v[70:71], v[164:165]
	v_pk_mul_f32 v[138:139], v[174:175], v[138:139]
	v_pk_fma_f32 v[160:161], v[66:67], v[160:161], v[164:165]
	s_waitcnt lgkmcnt(0)
	v_pk_mul_f32 v[164:165], v[134:135], v[168:169] op_sel_hi:[0,1]
	v_pk_fma_f32 v[160:161], v[74:75], v[164:165], v[160:161]
	ds_read_b128 v[172:175], v159 offset:2320
	ds_read_b128 v[176:179], v159 offset:2848
	s_waitcnt vmcnt(0)
	v_pk_add_f32 v[160:161], v[78:79], v[160:161]
	v_pk_mul_f32 v[162:163], v[0:1], v[162:163] op_sel_hi:[0,1]
	v_mul_f32_e32 v164, 0xbfb8aa3b, v160
	v_exp_f32_e32 v164, v164
	s_waitcnt lgkmcnt(1)
	v_pk_mul_f32 v[168:169], v[58:59], v[172:173]
	v_pk_mul_f32 v[166:167], v[72:73], v[166:167]
	v_pk_fma_f32 v[114:115], v[50:51], v[114:115], v[168:169]
	v_add_f32_e32 v159, 1.0, v164
	v_rcp_f32_e32 v164, v159
	v_mul_f32_e32 v159, 0xbfb8aa3b, v161
	v_exp_f32_e32 v159, v159
	s_waitcnt lgkmcnt(0)
	v_pk_mul_f32 v[168:169], v[134:135], v[176:177] op_sel_hi:[0,1]
	v_pk_fma_f32 v[162:163], v[68:69], v[162:163], v[166:167]
	v_pk_mul_f32 v[166:167], v[134:135], v[170:171] op_sel_hi:[0,1]
	v_add_f32_e32 v159, 1.0, v159
	v_rcp_f32_e32 v165, v159
	v_pk_fma_f32 v[114:115], v[54:55], v[168:169], v[114:115]
	v_pk_fma_f32 v[162:163], v[76:77], v[166:167], v[162:163]
	v_pk_add_f32 v[114:115], v[62:63], v[114:115]
	v_pk_add_f32 v[162:163], v[80:81], v[162:163]
	v_pk_mul_f32 v[160:161], v[160:161], v[164:165]
	v_mul_f32_e32 v159, 0xbfb8aa3b, v162
	v_pk_mul_f32 v[160:161], v[114:115], v[160:161]
	v_mul_f32_e32 v115, 0xbfb8aa3b, v163
	v_exp_f32_e32 v159, v159
	v_exp_f32_e32 v115, v115
	v_pk_mul_f32 v[164:165], v[60:61], v[174:175]
	s_movk_i32 s14, 0x1600
	v_add_f32_e32 v114, 1.0, v159
	v_add_f32_e32 v0, 1.0, v115
	v_rcp_f32_e32 v114, v114
	v_rcp_f32_e32 v115, v0
	v_pk_fma_f32 v[116:117], v[52:53], v[116:117], v[164:165]
	v_pk_mul_f32 v[164:165], v[134:135], v[178:179] op_sel_hi:[0,1]
	v_pk_fma_f32 v[116:117], v[56:57], v[164:165], v[116:117]
	v_pk_mul_f32 v[114:115], v[162:163], v[114:115]
	v_pk_add_f32 v[116:117], v[64:65], v[116:117]
	s_nop 0
	v_pk_mul_f32 v[162:163], v[116:117], v[114:115]
	v_cvt_pk_bf16_f32 v114, v136, v137
	v_cvt_pk_bf16_f32 v115, v138, v139
	v_cvt_pk_bf16_f32 v116, v160, v161
	v_cvt_pk_bf16_f32 v117, v162, v163
	v_mad_i64_i32 v[136:137], s[22:23], v158, s14, v[132:133]
	global_store_dwordx4 v[136:137], v[114:117], off
.LBB0_1079:
	s_or_b64 exec, exec, s[20:21]
	v_add_u32_e32 v159, 64, v158
	v_cmp_gt_i32_e32 vcc, s24, v159
	s_and_b64 s[22:23], s[6:7], vcc
	s_and_saveexec_b64 s[20:21], s[22:23]
	s_cbranch_execz .LBB0_1081
	v_cmp_gt_i32_e32 vcc, s39, v159
	s_nop 1
	v_cndmask_b32_e32 v114, v235, v236, vcc
	v_and_b32_e32 v115, v114, v159
	v_cmp_eq_u32_e64 s[100:101], 0, v115
	v_cmp_eq_u32_e32 vcc, v115, v114
	s_nop 3
	s_or_b64 s[100:101], s[100:101], vcc
	s_cbranch_scc0 .Lcf_1
	v_cmp_gt_i32_e32 vcc, s39, v159
	ds_read_b128 v[136:139], v156 offset:1904
	ds_read_b128 v[160:163], v156 offset:2432
	v_cndmask_b32_e32 v114, v235, v236, vcc
	v_and_b32_e32 v115, v114, v159
	ds_read_b128 v[164:167], v156 offset:2960
	ds_read_b128 v[168:171], v156 offset:1776
	v_cmp_eq_u32_e32 vcc, 0, v115
	s_waitcnt lgkmcnt(2)
	v_pk_mul_f32 v[116:117], v[102:103], v[160:161]
	v_pk_mul_f32 v[162:163], v[104:105], v[162:163]
	v_cndmask_b32_e64 v0, 1.0, 0, vcc
	v_cmp_eq_u32_e32 vcc, v115, v114
	v_pk_mul_f32 v[114:115], v[0:1], v[136:137] op_sel_hi:[0,1]
	v_pk_fma_f32 v[114:115], v[98:99], v[114:115], v[116:117]
	v_cndmask_b32_e64 v134, 1.0, 0, vcc
	s_waitcnt lgkmcnt(1)
	v_pk_mul_f32 v[116:117], v[134:135], v[164:165] op_sel_hi:[0,1]
	v_pk_fma_f32 v[114:115], v[106:107], v[116:117], v[114:115]
	v_pk_mul_f32 v[138:139], v[0:1], v[138:139] op_sel_hi:[0,1]
	v_pk_add_f32 v[136:137], v[110:111], v[114:115]
	v_pk_fma_f32 v[138:139], v[100:101], v[138:139], v[162:163]
	v_mul_f32_e32 v114, 0xbfb8aa3b, v136
	v_mul_f32_e32 v161, 0xbfb8aa3b, v137
	v_exp_f32_e32 v160, v114
	ds_read_b128 v[114:117], v156 offset:1792
	ds_read_b128 v[172:175], v156 offset:2304
	ds_read_b128 v[176:179], v156 offset:2832
	v_exp_f32_e32 v161, v161
	v_pk_mul_f32 v[162:163], v[134:135], v[166:167] op_sel_hi:[0,1]
	v_pk_fma_f32 v[138:139], v[108:109], v[162:163], v[138:139]
	v_add_f32_e32 v160, 1.0, v160
	v_pk_add_f32 v[138:139], v[112:113], v[138:139]
	s_waitcnt lgkmcnt(3)
	v_pk_mul_f32 v[164:165], v[0:1], v[168:169] op_sel_hi:[0,1]
	s_waitcnt lgkmcnt(1)
; DI unsigned pk2(float a, float b) { f32x2 v = {a, b}; bf16x2_t r = __builtin_convertvector(v, bf16x2_t); return __builtin_bit_cast(unsigned, r); }
; DI float silu_f(float g) { return g * rcpf_(1.f + ex2(-g * LOG2E)); }
; static __device__ __forceinline__ void phase_ffn_up(const P& p, int l, char* lds) {
;     ...
; #pragma unroll
;       for (int jj = 0; jj < 4; ++jj) {
;         const int r = (tid >> 3) + 64 * jj, tt = tstart + r;
;         if (r >= 1 && r <= 254 && tt < MEND) {
;           const int pos = tt < MLAT ? (tt & (TLAT - 1)) : ((tt - MLAT) & (TCTX - 1)), slen = tt < MLAT ? TLAT : TCTX;
;           const float fm = pos == 0 ? 0.f : 1.f, fp = pos == slen - 1 ? 0.f : 1.f;
;           const char* rp = tile + r * 528;
;           float o[8];
; #pragma unroll
;           for (int hf = 0; hf < 2; ++hf) {
;             const f32x4 am = *(const f32x4*)(rp - 528 + lca + hf * 16), a0 = *(const f32x4*)(rp + lca + hf * 16), ap = *(const f32x4*)(rp + 528 + lca + hf * 16);
;             const f32x4 gm = *(const f32x4*)(rp - 528 + lcg + hf * 16), g0 = *(const f32x4*)(rp + lcg + hf * 16), gp = *(const f32x4*)(rp + 528 + lcg + hf * 16);
; #pragma unroll
;             for (int e = 0; e < 4; ++e) {
;               const int q = hf * 4 + e;
;               const float ua = wa0[q] * (fm * am[e]) + wa1[q] * a0[e] + wa2[q] * (fp * ap[e]) + ba[q];
;               const float ug = wg0[q] * (fm * gm[e]) + wg1[q] * g0[e] + wg2[q] * (fp * gp[e]) + bg[q];
;               o[q] = silu_f(ug) * ua;
;             }
;           }
;           u32x4 w = {pk2(o[0], o[1]), pk2(o[2], o[3]), pk2(o[4], o[5]), pk2(o[6], o[7])};
;           *(u32x4*)(act + (size_t)tt * DFF + ca0) = w;
	v_pk_mul_f32 v[168:169], v[94:95], v[172:173]
	v_add_f32_e32 v161, 1.0, v161
	v_mul_f32_e32 v162, 0xbfb8aa3b, v138
	v_rcp_f32_e32 v160, v160
	v_pk_fma_f32 v[164:165], v[86:87], v[164:165], v[168:169]
	s_waitcnt lgkmcnt(0)
	v_pk_mul_f32 v[168:169], v[134:135], v[176:177] op_sel_hi:[0,1]
	v_rcp_f32_e32 v161, v161
	v_exp_f32_e32 v166, v162
	v_pk_fma_f32 v[164:165], v[90:91], v[168:169], v[164:165]
	v_pk_mul_f32 v[114:115], v[0:1], v[114:115] op_sel_hi:[0,1]
	v_pk_add_f32 v[162:163], v[82:83], v[164:165]
	v_mul_f32_e32 v164, 0xbfb8aa3b, v139
	v_exp_f32_e32 v164, v164
	v_pk_mul_f32 v[136:137], v[136:137], v[160:161]
	v_add_f32_e32 v160, 1.0, v166
	v_pk_mul_f32 v[136:137], v[162:163], v[136:137]
	v_rcp_f32_e32 v172, v160
	v_pk_mul_f32 v[160:161], v[0:1], v[170:171] op_sel_hi:[0,1]
	v_pk_mul_f32 v[162:163], v[96:97], v[174:175]
	v_pk_mul_f32 v[116:117], v[0:1], v[116:117] op_sel_hi:[0,1]
	v_pk_fma_f32 v[160:161], v[88:89], v[160:161], v[162:163]
	v_pk_mul_f32 v[162:163], v[134:135], v[178:179] op_sel_hi:[0,1]
	v_pk_fma_f32 v[168:169], v[92:93], v[162:163], v[160:161]
	v_add_f32_e32 v160, 1.0, v164
	v_rcp_f32_e32 v173, v160
	ds_read_b128 v[160:163], v156 offset:1920
	ds_read_b128 v[164:167], v156 offset:2448
	v_pk_add_f32 v[174:175], v[84:85], v[168:169]
	ds_read_b128 v[168:171], v156 offset:2976
	v_pk_mul_f32 v[138:139], v[138:139], v[172:173]
	s_waitcnt lgkmcnt(2)
	v_pk_mul_f32 v[160:161], v[0:1], v[160:161] op_sel_hi:[0,1]
	s_waitcnt lgkmcnt(1)
	v_pk_mul_f32 v[164:165], v[70:71], v[164:165]
	v_pk_mul_f32 v[138:139], v[174:175], v[138:139]
	v_pk_fma_f32 v[160:161], v[66:67], v[160:161], v[164:165]
	s_waitcnt lgkmcnt(0)
	v_pk_mul_f32 v[164:165], v[134:135], v[168:169] op_sel_hi:[0,1]
	v_pk_fma_f32 v[160:161], v[74:75], v[164:165], v[160:161]
	ds_read_b128 v[172:175], v156 offset:2320
	ds_read_b128 v[176:179], v156 offset:2848
	v_pk_add_f32 v[160:161], v[78:79], v[160:161]
	v_pk_mul_f32 v[162:163], v[0:1], v[162:163] op_sel_hi:[0,1]
	v_mul_f32_e32 v164, 0xbfb8aa3b, v160
	v_mul_f32_e32 v165, 0xbfb8aa3b, v161
	v_exp_f32_e32 v164, v164
	v_exp_f32_e32 v165, v165
	s_waitcnt lgkmcnt(1)
	v_pk_mul_f32 v[168:169], v[58:59], v[172:173]
	v_pk_mul_f32 v[166:167], v[72:73], v[166:167]
	v_add_f32_e32 v164, 1.0, v164
	v_add_f32_e32 v165, 1.0, v165
	v_rcp_f32_e32 v164, v164
	v_rcp_f32_e32 v165, v165
	v_pk_fma_f32 v[114:115], v[50:51], v[114:115], v[168:169]
	s_waitcnt lgkmcnt(0)
	v_pk_mul_f32 v[168:169], v[134:135], v[176:177] op_sel_hi:[0,1]
	v_pk_fma_f32 v[162:163], v[68:69], v[162:163], v[166:167]
	v_pk_mul_f32 v[166:167], v[134:135], v[170:171] op_sel_hi:[0,1]
	v_pk_fma_f32 v[114:115], v[54:55], v[168:169], v[114:115]
	v_pk_fma_f32 v[162:163], v[76:77], v[166:167], v[162:163]
	v_pk_add_f32 v[114:115], v[62:63], v[114:115]
	v_pk_add_f32 v[162:163], v[80:81], v[162:163]
	v_pk_mul_f32 v[160:161], v[160:161], v[164:165]
	v_mul_f32_e32 v166, 0xbfb8aa3b, v162
	v_pk_mul_f32 v[160:161], v[114:115], v[160:161]
	v_mul_f32_e32 v115, 0xbfb8aa3b, v163
	v_exp_f32_e32 v166, v166
	v_exp_f32_e32 v115, v115
	v_pk_mul_f32 v[164:165], v[60:61], v[174:175]
	s_movk_i32 s14, 0x1600
	v_add_f32_e32 v114, 1.0, v166
	v_add_f32_e32 v0, 1.0, v115
	v_rcp_f32_e32 v114, v114
	v_rcp_f32_e32 v115, v0
	v_pk_fma_f32 v[116:117], v[52:53], v[116:117], v[164:165]
	v_pk_mul_f32 v[164:165], v[134:135], v[178:179] op_sel_hi:[0,1]
	v_pk_fma_f32 v[116:117], v[56:57], v[164:165], v[116:117]
	v_pk_mul_f32 v[114:115], v[162:163], v[114:115]
	v_pk_add_f32 v[116:117], v[64:65], v[116:117]
	s_nop 0
	v_pk_mul_f32 v[162:163], v[116:117], v[114:115]
	v_cvt_pk_bf16_f32 v114, v136, v137
	v_cvt_pk_bf16_f32 v115, v138, v139
	v_cvt_pk_bf16_f32 v116, v160, v161
	v_cvt_pk_bf16_f32 v117, v162, v163
	v_mad_i64_i32 v[136:137], s[22:23], v159, s14, v[132:133]
	global_store_dwordx4 v[136:137], v[114:117], off
.LBB0_1081:
	s_or_b64 exec, exec, s[20:21]
	v_add_u32_e32 v159, 0x80, v158
	v_cmp_gt_i32_e32 vcc, s24, v159
	s_and_b64 s[22:23], s[8:9], vcc
	s_and_saveexec_b64 s[20:21], s[22:23]
	s_cbranch_execz .LBB0_1083
	v_cmp_gt_i32_e32 vcc, s39, v159
	s_nop 1
	v_cndmask_b32_e32 v114, v235, v236, vcc
	v_and_b32_e32 v115, v114, v159
	v_cmp_eq_u32_e64 s[100:101], 0, v115
	v_cmp_eq_u32_e32 vcc, v115, v114
	s_nop 3
	s_or_b64 s[100:101], s[100:101], vcc
	s_cbranch_scc0 .Lcf_2
; DI unsigned pk2(float a, float b) { f32x2 v = {a, b}; bf16x2_t r = __builtin_convertvector(v, bf16x2_t); return __builtin_bit_cast(unsigned, r); }
; DI float silu_f(float g) { return g * rcpf_(1.f + ex2(-g * LOG2E)); }
; static __device__ __forceinline__ void phase_ffn_up(const P& p, int l, char* lds) {
;     ...
;         const int r = (tid >> 3) + 64 * jj, tt = tstart + r;
;         if (r >= 1 && r <= 254 && tt < MEND) {
;           const int pos = tt < MLAT ? (tt & (TLAT - 1)) : ((tt - MLAT) & (TCTX - 1)), slen = tt < MLAT ? TLAT : TCTX;
;           const float fm = pos == 0 ? 0.f : 1.f, fp = pos == slen - 1 ? 0.f : 1.f;
;           const char* rp = tile + r * 528;
;           float o[8];
; #pragma unroll
;           for (int hf = 0; hf < 2; ++hf) {
;             const f32x4 am = *(const f32x4*)(rp - 528 + lca + hf * 16), a0 = *(const f32x4*)(rp + lca + hf * 16), ap = *(const f32x4*)(rp + 528 + lca + hf * 16);
;             const f32x4 gm = *(const f32x4*)(rp - 528 + lcg + hf * 16), g0 = *(const f32x4*)(rp + lcg + hf * 16), gp = *(const f32x4*)(rp + 528 + lcg + hf * 16);
; #pragma unroll
;             for (int e = 0; e < 4; ++e) {
;               const int q = hf * 4 + e;
;               const float ua = wa0[q] * (fm * am[e]) + wa1[q] * a0[e] + wa2[q] * (fp * ap[e]) + ba[q];
;               const float ug = wg0[q] * (fm * gm[e]) + wg1[q] * g0[e] + wg2[q] * (fp * gp[e]) + bg[q];
;               o[q] = silu_f(ug) * ua;
;             }
;           }
;           u32x4 w = {pk2(o[0], o[1]), pk2(o[2], o[3]), pk2(o[4], o[5]), pk2(o[6], o[7])};
;           *(u32x4*)(act + (size_t)tt * DFF + ca0) = w;
	v_cmp_gt_i32_e32 vcc, s39, v159
	ds_read_b128 v[136:139], v157 offset:1904
	ds_read_b128 v[160:163], v157 offset:2432
	v_cndmask_b32_e32 v114, v235, v236, vcc
	v_and_b32_e32 v115, v114, v159
	ds_read_b128 v[164:167], v157 offset:2960
	ds_read_b128 v[168:171], v157 offset:1776
	v_cmp_eq_u32_e32 vcc, 0, v115
	s_waitcnt lgkmcnt(2)
	v_pk_mul_f32 v[116:117], v[102:103], v[160:161]
	v_pk_mul_f32 v[162:163], v[104:105], v[162:163]
	v_cndmask_b32_e64 v0, 1.0, 0, vcc
	v_cmp_eq_u32_e32 vcc, v115, v114
	v_pk_mul_f32 v[114:115], v[0:1], v[136:137] op_sel_hi:[0,1]
	v_pk_fma_f32 v[114:115], v[98:99], v[114:115], v[116:117]
	v_cndmask_b32_e64 v134, 1.0, 0, vcc
	s_waitcnt lgkmcnt(1)
	v_pk_mul_f32 v[116:117], v[134:135], v[164:165] op_sel_hi:[0,1]
	v_pk_fma_f32 v[114:115], v[106:107], v[116:117], v[114:115]
	v_pk_mul_f32 v[138:139], v[0:1], v[138:139] op_sel_hi:[0,1]
	v_pk_add_f32 v[136:137], v[110:111], v[114:115]
	v_pk_fma_f32 v[138:139], v[100:101], v[138:139], v[162:163]
	v_mul_f32_e32 v114, 0xbfb8aa3b, v136
	v_mul_f32_e32 v161, 0xbfb8aa3b, v137
	v_exp_f32_e32 v160, v114
	ds_read_b128 v[114:117], v157 offset:1792
	ds_read_b128 v[172:175], v157 offset:2304
	ds_read_b128 v[176:179], v157 offset:2832
	v_exp_f32_e32 v161, v161
	v_pk_mul_f32 v[162:163], v[134:135], v[166:167] op_sel_hi:[0,1]
	v_pk_fma_f32 v[138:139], v[108:109], v[162:163], v[138:139]
	v_add_f32_e32 v160, 1.0, v160
	v_pk_add_f32 v[138:139], v[112:113], v[138:139]
	s_waitcnt lgkmcnt(3)
	v_pk_mul_f32 v[164:165], v[0:1], v[168:169] op_sel_hi:[0,1]
	s_waitcnt lgkmcnt(1)
	v_pk_mul_f32 v[168:169], v[94:95], v[172:173]
	v_add_f32_e32 v161, 1.0, v161
	v_mul_f32_e32 v162, 0xbfb8aa3b, v138
	v_rcp_f32_e32 v160, v160
	v_pk_fma_f32 v[164:165], v[86:87], v[164:165], v[168:169]
	s_waitcnt lgkmcnt(0)
	v_pk_mul_f32 v[168:169], v[134:135], v[176:177] op_sel_hi:[0,1]
	v_rcp_f32_e32 v161, v161
	v_exp_f32_e32 v166, v162
	v_pk_fma_f32 v[164:165], v[90:91], v[168:169], v[164:165]
	v_pk_mul_f32 v[114:115], v[0:1], v[114:115] op_sel_hi:[0,1]
	v_pk_add_f32 v[162:163], v[82:83], v[164:165]
	v_mul_f32_e32 v164, 0xbfb8aa3b, v139
	v_exp_f32_e32 v164, v164
	v_pk_mul_f32 v[136:137], v[136:137], v[160:161]
	v_add_f32_e32 v160, 1.0, v166
	v_pk_mul_f32 v[136:137], v[162:163], v[136:137]
	v_rcp_f32_e32 v172, v160
	v_pk_mul_f32 v[160:161], v[0:1], v[170:171] op_sel_hi:[0,1]
	v_pk_mul_f32 v[162:163], v[96:97], v[174:175]
	v_pk_mul_f32 v[116:117], v[0:1], v[116:117] op_sel_hi:[0,1]
	v_pk_fma_f32 v[160:161], v[88:89], v[160:161], v[162:163]
	v_pk_mul_f32 v[162:163], v[134:135], v[178:179] op_sel_hi:[0,1]
	v_pk_fma_f32 v[168:169], v[92:93], v[162:163], v[160:161]
	v_add_f32_e32 v160, 1.0, v164
	v_rcp_f32_e32 v173, v160
	ds_read_b128 v[160:163], v157 offset:1920
	ds_read_b128 v[164:167], v157 offset:2448
	v_pk_add_f32 v[174:175], v[84:85], v[168:169]
	ds_read_b128 v[168:171], v157 offset:2976
	v_pk_mul_f32 v[138:139], v[138:139], v[172:173]
	s_waitcnt lgkmcnt(2)
	v_pk_mul_f32 v[160:161], v[0:1], v[160:161] op_sel_hi:[0,1]
	s_waitcnt lgkmcnt(1)
	v_pk_mul_f32 v[164:165], v[70:71], v[164:165]
	v_pk_mul_f32 v[138:139], v[174:175], v[138:139]
	v_pk_fma_f32 v[160:161], v[66:67], v[160:161], v[164:165]
	s_waitcnt lgkmcnt(0)
	v_pk_mul_f32 v[164:165], v[134:135], v[168:169] op_sel_hi:[0,1]
	v_pk_fma_f32 v[160:161], v[74:75], v[164:165], v[160:161]
	ds_read_b128 v[172:175], v157 offset:2320
	ds_read_b128 v[176:179], v157 offset:2848
	v_pk_add_f32 v[160:161], v[78:79], v[160:161]
	v_pk_mul_f32 v[162:163], v[0:1], v[162:163] op_sel_hi:[0,1]
	v_mul_f32_e32 v164, 0xbfb8aa3b, v160
	v_mul_f32_e32 v165, 0xbfb8aa3b, v161
	v_exp_f32_e32 v164, v164
	v_exp_f32_e32 v165, v165
	s_waitcnt lgkmcnt(1)
	v_pk_mul_f32 v[168:169], v[58:59], v[172:173]
	v_pk_mul_f32 v[166:167], v[72:73], v[166:167]
	v_add_f32_e32 v164, 1.0, v164
	v_add_f32_e32 v165, 1.0, v165
	v_rcp_f32_e32 v164, v164
	v_rcp_f32_e32 v165, v165
	v_pk_fma_f32 v[114:115], v[50:51], v[114:115], v[168:169]
	s_waitcnt lgkmcnt(0)
	v_pk_mul_f32 v[168:169], v[134:135], v[176:177] op_sel_hi:[0,1]
	v_pk_fma_f32 v[162:163], v[68:69], v[162:163], v[166:167]
	v_pk_mul_f32 v[166:167], v[134:135], v[170:171] op_sel_hi:[0,1]
	v_pk_fma_f32 v[114:115], v[54:55], v[168:169], v[114:115]
	v_pk_fma_f32 v[162:163], v[76:77], v[166:167], v[162:163]
	v_pk_add_f32 v[114:115], v[62:63], v[114:115]
	v_pk_add_f32 v[162:163], v[80:81], v[162:163]
	v_pk_mul_f32 v[160:161], v[160:161], v[164:165]
	v_mul_f32_e32 v166, 0xbfb8aa3b, v162
	v_pk_mul_f32 v[160:161], v[114:115], v[160:161]
	v_mul_f32_e32 v115, 0xbfb8aa3b, v163
	v_exp_f32_e32 v166, v166
	v_exp_f32_e32 v115, v115
	v_pk_mul_f32 v[164:165], v[60:61], v[174:175]
	s_movk_i32 s14, 0x1600
	v_add_f32_e32 v114, 1.0, v166
	v_add_f32_e32 v0, 1.0, v115
	v_rcp_f32_e32 v114, v114
	v_rcp_f32_e32 v115, v0
	v_pk_fma_f32 v[116:117], v[52:53], v[116:117], v[164:165]
	v_pk_mul_f32 v[164:165], v[134:135], v[178:179] op_sel_hi:[0,1]
	v_pk_fma_f32 v[116:117], v[56:57], v[164:165], v[116:117]
	v_pk_mul_f32 v[114:115], v[162:163], v[114:115]
	v_pk_add_f32 v[116:117], v[64:65], v[116:117]
	s_nop 0
	v_pk_mul_f32 v[162:163], v[116:117], v[114:115]
	v_cvt_pk_bf16_f32 v114, v136, v137
	v_cvt_pk_bf16_f32 v115, v138, v139
	v_cvt_pk_bf16_f32 v116, v160, v161
	v_cvt_pk_bf16_f32 v117, v162, v163
	v_mad_i64_i32 v[136:137], s[22:23], v159, s14, v[132:133]
	global_store_dwordx4 v[136:137], v[114:117], off
; DI unsigned pk2(float a, float b) { f32x2 v = {a, b}; bf16x2_t r = __builtin_convertvector(v, bf16x2_t); return __builtin_bit_cast(unsigned, r); }
; DI float silu_f(float g) { return g * rcpf_(1.f + ex2(-g * LOG2E)); }
; static __device__ __forceinline__ void phase_ffn_up(const P& p, int l, char* lds) {
;     ...
; #pragma unroll
;       for (int jj = 0; jj < 4; ++jj) {
;         const int r = (tid >> 3) + 64 * jj, tt = tstart + r;
;         if (r >= 1 && r <= 254 && tt < MEND) {
;           const int pos = tt < MLAT ? (tt & (TLAT - 1)) : ((tt - MLAT) & (TCTX - 1)), slen = tt < MLAT ? TLAT : TCTX;
;           const float fm = pos == 0 ? 0.f : 1.f, fp = pos == slen - 1 ? 0.f : 1.f;
;           const char* rp = tile + r * 528;
;           float o[8];
; #pragma unroll
;           for (int hf = 0; hf < 2; ++hf) {
;             const f32x4 am = *(const f32x4*)(rp - 528 + lca + hf * 16), a0 = *(const f32x4*)(rp + lca + hf * 16), ap = *(const f32x4*)(rp + 528 + lca + hf * 16);
;             const f32x4 gm = *(const f32x4*)(rp - 528 + lcg + hf * 16), g0 = *(const f32x4*)(rp + lcg + hf * 16), gp = *(const f32x4*)(rp + 528 + lcg + hf * 16);
; #pragma unroll
;             for (int e = 0; e < 4; ++e) {
;               const int q = hf * 4 + e;
;               const float ua = wa0[q] * (fm * am[e]) + wa1[q] * a0[e] + wa2[q] * (fp * ap[e]) + ba[q];
;               const float ug = wg0[q] * (fm * gm[e]) + wg1[q] * g0[e] + wg2[q] * (fp * gp[e]) + bg[q];
;               o[q] = silu_f(ug) * ua;
;             }
;           }
;           u32x4 w = {pk2(o[0], o[1]), pk2(o[2], o[3]), pk2(o[4], o[5]), pk2(o[6], o[7])};
;           *(u32x4*)(act + (size_t)tt * DFF + ca0) = w;
.LBB0_1083:
	s_or_b64 exec, exec, s[20:21]
	v_add_u32_e32 v136, 0xc0, v158
	v_cmp_gt_i32_e32 vcc, s24, v136
	s_and_b64 s[22:23], s[10:11], vcc
	s_and_saveexec_b64 s[20:21], s[22:23]
	s_cbranch_execz .LBB0_1058
	v_cmp_gt_i32_e32 vcc, s39, v136
	s_nop 1
	v_cndmask_b32_e32 v114, v235, v236, vcc
	v_and_b32_e32 v115, v114, v136
	v_cmp_eq_u32_e64 s[100:101], 0, v115
	v_cmp_eq_u32_e32 vcc, v115, v114
	s_nop 3
	s_or_b64 s[100:101], s[100:101], vcc
	s_cbranch_scc0 .Lcf_3
	v_cmp_gt_i32_e32 vcc, s39, v136
	ds_read_b128 v[158:161], v157 offset:35696
	ds_read_b128 v[162:165], v157 offset:36224
	v_cndmask_b32_e32 v114, v235, v236, vcc
	v_and_b32_e32 v115, v114, v136
	ds_read_b128 v[166:169], v157 offset:36752
	ds_read_b128 v[170:173], v157 offset:35568
	v_cmp_eq_u32_e32 vcc, 0, v115
	s_waitcnt lgkmcnt(2)
	v_pk_mul_f32 v[102:103], v[102:103], v[162:163]
	s_movk_i32 s14, 0x1600
	v_cndmask_b32_e64 v0, 1.0, 0, vcc
	v_cmp_eq_u32_e32 vcc, v115, v114
	v_pk_mul_f32 v[114:115], v[0:1], v[158:159] op_sel_hi:[0,1]
	v_pk_fma_f32 v[98:99], v[98:99], v[114:115], v[102:103]
	v_cndmask_b32_e64 v134, 1.0, 0, vcc
	s_waitcnt lgkmcnt(1)
	v_pk_mul_f32 v[102:103], v[134:135], v[166:167] op_sel_hi:[0,1]
	v_pk_fma_f32 v[98:99], v[106:107], v[102:103], v[98:99]
	ds_read_b128 v[114:117], v157 offset:35584
	ds_read_b128 v[174:177], v157 offset:36096
	ds_read_b128 v[178:181], v157 offset:36624
	v_pk_add_f32 v[98:99], v[110:111], v[98:99]
	s_waitcnt lgkmcnt(3)
	v_pk_mul_f32 v[106:107], v[0:1], v[170:171] op_sel_hi:[0,1]
	v_mul_f32_e32 v103, 0xbfb8aa3b, v99
	v_exp_f32_e32 v103, v103
	s_waitcnt lgkmcnt(1)
	v_pk_mul_f32 v[94:95], v[94:95], v[174:175]
	v_mul_f32_e32 v102, 0xbfb8aa3b, v98
	v_pk_fma_f32 v[86:87], v[86:87], v[106:107], v[94:95]
	s_waitcnt lgkmcnt(0)
	v_pk_mul_f32 v[94:95], v[134:135], v[178:179] op_sel_hi:[0,1]
	v_exp_f32_e32 v102, v102
	v_pk_fma_f32 v[86:87], v[90:91], v[94:95], v[86:87]
	v_add_f32_e32 v90, 1.0, v103
	v_rcp_f32_e32 v103, v90
	v_pk_mul_f32 v[90:91], v[0:1], v[160:161] op_sel_hi:[0,1]
	v_pk_mul_f32 v[94:95], v[104:105], v[164:165]
	v_add_f32_e32 v102, 1.0, v102
	v_pk_fma_f32 v[90:91], v[100:101], v[90:91], v[94:95]
	v_pk_mul_f32 v[94:95], v[134:135], v[168:169] op_sel_hi:[0,1]
	v_pk_fma_f32 v[90:91], v[108:109], v[94:95], v[90:91]
	v_rcp_f32_e32 v102, v102
	v_pk_add_f32 v[100:101], v[112:113], v[90:91]
	v_pk_add_f32 v[82:83], v[82:83], v[86:87]
	v_mul_f32_e32 v90, 0xbfb8aa3b, v100
	v_exp_f32_e32 v90, v90
	v_pk_mul_f32 v[86:87], v[98:99], v[102:103]
	v_mul_f32_e32 v94, 0xbfb8aa3b, v101
	v_pk_mul_f32 v[82:83], v[82:83], v[86:87]
	v_add_f32_e32 v86, 1.0, v90
	v_pk_mul_f32 v[90:91], v[96:97], v[176:177]
	v_exp_f32_e32 v96, v94
	v_rcp_f32_e32 v98, v86
	v_pk_mul_f32 v[86:87], v[0:1], v[172:173] op_sel_hi:[0,1]
	v_pk_fma_f32 v[86:87], v[88:89], v[86:87], v[90:91]
	v_pk_mul_f32 v[88:89], v[134:135], v[180:181] op_sel_hi:[0,1]
	v_pk_fma_f32 v[94:95], v[92:93], v[88:89], v[86:87]
	v_add_f32_e32 v86, 1.0, v96
	v_rcp_f32_e32 v99, v86
	ds_read_b128 v[86:89], v157 offset:35712
	ds_read_b128 v[90:93], v157 offset:36240
	v_pk_add_f32 v[84:85], v[84:85], v[94:95]
	ds_read_b128 v[94:97], v157 offset:36768
	v_pk_mul_f32 v[98:99], v[100:101], v[98:99]
	s_waitcnt lgkmcnt(2)
	v_pk_mul_f32 v[86:87], v[0:1], v[86:87] op_sel_hi:[0,1]
	s_waitcnt lgkmcnt(1)
	v_pk_mul_f32 v[70:71], v[70:71], v[90:91]
	s_nop 0
	v_pk_fma_f32 v[66:67], v[66:67], v[86:87], v[70:71]
	s_waitcnt lgkmcnt(0)
	v_pk_mul_f32 v[70:71], v[134:135], v[94:95] op_sel_hi:[0,1]
	v_pk_fma_f32 v[66:67], v[74:75], v[70:71], v[66:67]
	v_pk_add_f32 v[70:71], v[78:79], v[66:67]
	v_pk_mul_f32 v[78:79], v[0:1], v[114:115] op_sel_hi:[0,1]
	v_mul_f32_e32 v66, 0xbfb8aa3b, v70
	v_exp_f32_e32 v74, v66
	v_pk_mul_f32 v[66:67], v[84:85], v[98:99]
	ds_read_b128 v[84:87], v157 offset:36112
	ds_read_b128 v[98:101], v157 offset:36640
	v_mul_f32_e32 v75, 0xbfb8aa3b, v71
	v_exp_f32_e32 v75, v75
	v_add_f32_e32 v74, 1.0, v74
	s_waitcnt lgkmcnt(1)
	v_pk_mul_f32 v[58:59], v[58:59], v[84:85]
	v_rcp_f32_e32 v74, v74
	v_pk_fma_f32 v[50:51], v[50:51], v[78:79], v[58:59]
	s_waitcnt lgkmcnt(0)
	v_pk_mul_f32 v[58:59], v[134:135], v[98:99] op_sel_hi:[0,1]
	v_pk_fma_f32 v[50:51], v[54:55], v[58:59], v[50:51]
	v_add_f32_e32 v54, 1.0, v75
	v_rcp_f32_e32 v75, v54
	v_pk_mul_f32 v[54:55], v[0:1], v[88:89] op_sel_hi:[0,1]
	v_pk_mul_f32 v[58:59], v[72:73], v[92:93]
	v_pk_add_f32 v[50:51], v[62:63], v[50:51]
	v_pk_fma_f32 v[54:55], v[68:69], v[54:55], v[58:59]
	v_pk_mul_f32 v[58:59], v[134:135], v[96:97] op_sel_hi:[0,1]
	v_pk_fma_f32 v[54:55], v[76:77], v[58:59], v[54:55]
	v_pk_mul_f32 v[62:63], v[0:1], v[116:117] op_sel_hi:[0,1]
	v_pk_add_f32 v[54:55], v[80:81], v[54:55]
	v_pk_mul_f32 v[60:61], v[60:61], v[86:87]
	v_mul_f32_e32 v58, 0xbfb8aa3b, v54
	v_exp_f32_e32 v68, v58
	v_pk_mul_f32 v[58:59], v[70:71], v[74:75]
	v_pk_fma_f32 v[52:53], v[52:53], v[62:63], v[60:61]
	v_pk_mul_f32 v[58:59], v[50:51], v[58:59]
	v_mul_f32_e32 v51, 0xbfb8aa3b, v55
	v_exp_f32_e32 v51, v51
	v_add_f32_e32 v50, 1.0, v68
	v_rcp_f32_e32 v50, v50
	v_pk_mul_f32 v[60:61], v[134:135], v[100:101] op_sel_hi:[0,1]
	v_add_f32_e32 v0, 1.0, v51
	v_rcp_f32_e32 v51, v0
	v_pk_fma_f32 v[52:53], v[56:57], v[60:61], v[52:53]
	v_pk_mul_f32 v[50:51], v[54:55], v[50:51]
	v_pk_add_f32 v[52:53], v[64:65], v[52:53]
	s_nop 0
	v_pk_mul_f32 v[54:55], v[52:53], v[50:51]
	v_cvt_pk_bf16_f32 v50, v82, v83
	v_cvt_pk_bf16_f32 v51, v66, v67
	v_cvt_pk_bf16_f32 v52, v58, v59
	v_cvt_pk_bf16_f32 v53, v54, v55
	v_mad_i64_i32 v[54:55], s[22:23], v136, s14, v[132:133]
	global_store_dwordx4 v[54:55], v[50:53], off
	s_branch .LBB0_1058
; DI unsigned pk2(float a, float b) { f32x2 v = {a, b}; bf16x2_t r = __builtin_convertvector(v, bf16x2_t); return __builtin_bit_cast(unsigned, r); }
; DI float silu_f(float g) { return g * rcpf_(1.f + ex2(-g * LOG2E)); }
; static __device__ __forceinline__ void phase_ffn_up(const P& p, int l, char* lds) {
;     ...
; #pragma unroll
;           for (int hf = 0; hf < 2; ++hf) {
;             const f32x4 am = *(const f32x4*)(rp - 528 + lca + hf * 16), a0 = *(const f32x4*)(rp + lca + hf * 16), ap = *(const f32x4*)(rp + 528 + lca + hf * 16);
;             const f32x4 gm = *(const f32x4*)(rp - 528 + lcg + hf * 16), g0 = *(const f32x4*)(rp + lcg + hf * 16), gp = *(const f32x4*)(rp + 528 + lcg + hf * 16);
; #pragma unroll
;             for (int e = 0; e < 4; ++e) {
;               const int q = hf * 4 + e;
;               const float ua = wa0[q] * (fm * am[e]) + wa1[q] * a0[e] + wa2[q] * (fp * ap[e]) + ba[q];
;               const float ug = wg0[q] * (fm * gm[e]) + wg1[q] * g0[e] + wg2[q] * (fp * gp[e]) + bg[q];
;               o[q] = silu_f(ug) * ua;
;             }
;           }
;           u32x4 w = {pk2(o[0], o[1]), pk2(o[2], o[3]), pk2(o[4], o[5]), pk2(o[6], o[7])};
;           *(u32x4*)(act + (size_t)tt * DFF + ca0) = w;
.Lcf_0:
	v_mov_b32_e32 v0, v158
	s_mov_b32 s100, 0xbfb8aa3b
	s_mov_b32 s101, 0xbfb8aa3b
	ds_read_b128 v[160:163], v159 offset:1904
	ds_read_b128 v[164:167], v159 offset:2432
	ds_read_b128 v[168:171], v159 offset:2960
	ds_read_b128 v[172:175], v159 offset:1776
	ds_read_b128 v[176:179], v159 offset:2304
	ds_read_b128 v[136:139], v159 offset:2832
	ds_read_b128 v[182:185], v159 offset:1920
	ds_read_b128 v[186:189], v159 offset:2448
	ds_read_b128 v[190:193], v159 offset:2976
	ds_read_b128 v[194:197], v159 offset:1792
	ds_read_b128 v[200:203], v159 offset:2320
	ds_read_b128 v[204:207], v159 offset:2848
	s_waitcnt lgkmcnt(11)
	v_pk_fma_f32 v[160:161], v[98:99], v[160:161], v[110:111]
	v_pk_fma_f32 v[162:163], v[100:101], v[162:163], v[112:113]
	s_waitcnt lgkmcnt(10)
	v_pk_fma_f32 v[160:161], v[102:103], v[164:165], v[160:161]
	v_pk_fma_f32 v[162:163], v[104:105], v[166:167], v[162:163]
	s_waitcnt lgkmcnt(9)
	v_pk_fma_f32 v[160:161], v[106:107], v[168:169], v[160:161]
	v_pk_fma_f32 v[162:163], v[108:109], v[170:171], v[162:163]
	v_pk_mul_f32 v[164:165], v[160:161], s[100:101]
	v_pk_mul_f32 v[166:167], v[162:163], s[100:101]
	v_exp_f32_e32 v164, v164
	v_exp_f32_e32 v165, v165
	v_exp_f32_e32 v166, v166
	v_exp_f32_e32 v167, v167
	s_waitcnt lgkmcnt(8)
	v_pk_fma_f32 v[172:173], v[86:87], v[172:173], v[82:83]
	v_pk_fma_f32 v[174:175], v[88:89], v[174:175], v[84:85]
	s_waitcnt lgkmcnt(7)
	v_pk_fma_f32 v[172:173], v[94:95], v[176:177], v[172:173]
	v_pk_fma_f32 v[174:175], v[96:97], v[178:179], v[174:175]
	s_waitcnt lgkmcnt(6)
	v_pk_fma_f32 v[172:173], v[90:91], v[136:137], v[172:173]
	v_pk_fma_f32 v[174:175], v[92:93], v[138:139], v[174:175]
	v_add_f32_e32 v164, 1.0, v164
	v_add_f32_e32 v165, 1.0, v165
	v_add_f32_e32 v166, 1.0, v166
	v_add_f32_e32 v167, 1.0, v167
	s_waitcnt lgkmcnt(5)
	v_pk_fma_f32 v[182:183], v[66:67], v[182:183], v[78:79]
	v_pk_fma_f32 v[184:185], v[68:69], v[184:185], v[80:81]
	s_waitcnt lgkmcnt(4)
	v_pk_fma_f32 v[182:183], v[70:71], v[186:187], v[182:183]
	v_pk_fma_f32 v[184:185], v[72:73], v[188:189], v[184:185]
	s_waitcnt lgkmcnt(3)
	v_pk_fma_f32 v[182:183], v[74:75], v[190:191], v[182:183]
	v_pk_fma_f32 v[184:185], v[76:77], v[192:193], v[184:185]
	v_rcp_f32_e32 v164, v164
	v_rcp_f32_e32 v165, v165
	v_rcp_f32_e32 v166, v166
	v_rcp_f32_e32 v167, v167
	v_pk_mul_f32 v[186:187], v[182:183], s[100:101]
	v_pk_mul_f32 v[188:189], v[184:185], s[100:101]
	v_exp_f32_e32 v186, v186
	v_exp_f32_e32 v187, v187
	v_exp_f32_e32 v188, v188
	v_exp_f32_e32 v189, v189
	s_waitcnt lgkmcnt(2)
	v_pk_fma_f32 v[194:195], v[50:51], v[194:195], v[62:63]
	v_pk_fma_f32 v[196:197], v[52:53], v[196:197], v[64:65]
	s_waitcnt lgkmcnt(1)
	v_pk_fma_f32 v[194:195], v[58:59], v[200:201], v[194:195]
	v_pk_fma_f32 v[196:197], v[60:61], v[202:203], v[196:197]
	s_waitcnt lgkmcnt(0)
	v_pk_fma_f32 v[194:195], v[54:55], v[204:205], v[194:195]
	v_pk_fma_f32 v[196:197], v[56:57], v[206:207], v[196:197]
	v_pk_mul_f32 v[160:161], v[160:161], v[164:165]
	v_pk_mul_f32 v[162:163], v[162:163], v[166:167]
	v_pk_mul_f32 v[160:161], v[172:173], v[160:161]
	v_pk_mul_f32 v[162:163], v[174:175], v[162:163]
	v_cvt_pk_bf16_f32 v114, v160, v161
	v_cvt_pk_bf16_f32 v115, v162, v163
	v_add_f32_e32 v186, 1.0, v186
	v_add_f32_e32 v187, 1.0, v187
	v_add_f32_e32 v188, 1.0, v188
	v_add_f32_e32 v189, 1.0, v189
	v_rcp_f32_e32 v186, v186
	v_rcp_f32_e32 v187, v187
	v_rcp_f32_e32 v188, v188
	v_rcp_f32_e32 v189, v189
	s_movk_i32 s14, 0x1600
	v_mad_i64_i32 v[136:137], s[22:23], v0, s14, v[132:133]
	v_pk_mul_f32 v[182:183], v[182:183], v[186:187]
	v_pk_mul_f32 v[184:185], v[184:185], v[188:189]
	v_pk_mul_f32 v[182:183], v[194:195], v[182:183]
	v_pk_mul_f32 v[184:185], v[196:197], v[184:185]
	v_cvt_pk_bf16_f32 v116, v182, v183
	v_cvt_pk_bf16_f32 v117, v184, v185
	global_store_dwordx4 v[136:137], v[114:117], off
	s_branch .LBB0_1079
.Lcf_1:
	v_mov_b32_e32 v0, v159
	s_mov_b32 s100, 0xbfb8aa3b
	s_mov_b32 s101, 0xbfb8aa3b
	ds_read_b128 v[160:163], v156 offset:1904
	ds_read_b128 v[164:167], v156 offset:2432
	ds_read_b128 v[168:171], v156 offset:2960
	ds_read_b128 v[172:175], v156 offset:1776
	ds_read_b128 v[176:179], v156 offset:2304
	ds_read_b128 v[136:139], v156 offset:2832
	ds_read_b128 v[182:185], v156 offset:1920
	ds_read_b128 v[186:189], v156 offset:2448
	ds_read_b128 v[190:193], v156 offset:2976
	ds_read_b128 v[194:197], v156 offset:1792
	ds_read_b128 v[200:203], v156 offset:2320
	ds_read_b128 v[204:207], v156 offset:2848
	s_waitcnt lgkmcnt(11)
	v_pk_fma_f32 v[160:161], v[98:99], v[160:161], v[110:111]
	v_pk_fma_f32 v[162:163], v[100:101], v[162:163], v[112:113]
	s_waitcnt lgkmcnt(10)
	v_pk_fma_f32 v[160:161], v[102:103], v[164:165], v[160:161]
	v_pk_fma_f32 v[162:163], v[104:105], v[166:167], v[162:163]
	s_waitcnt lgkmcnt(9)
	v_pk_fma_f32 v[160:161], v[106:107], v[168:169], v[160:161]
	v_pk_fma_f32 v[162:163], v[108:109], v[170:171], v[162:163]
	v_pk_mul_f32 v[164:165], v[160:161], s[100:101]
	v_pk_mul_f32 v[166:167], v[162:163], s[100:101]
	v_exp_f32_e32 v164, v164
	v_exp_f32_e32 v165, v165
	v_exp_f32_e32 v166, v166
	v_exp_f32_e32 v167, v167
	s_waitcnt lgkmcnt(8)
	v_pk_fma_f32 v[172:173], v[86:87], v[172:173], v[82:83]
	v_pk_fma_f32 v[174:175], v[88:89], v[174:175], v[84:85]
	s_waitcnt lgkmcnt(7)
	v_pk_fma_f32 v[172:173], v[94:95], v[176:177], v[172:173]
	v_pk_fma_f32 v[174:175], v[96:97], v[178:179], v[174:175]
	s_waitcnt lgkmcnt(6)
	v_pk_fma_f32 v[172:173], v[90:91], v[136:137], v[172:173]
	v_pk_fma_f32 v[174:175], v[92:93], v[138:139], v[174:175]
	v_add_f32_e32 v164, 1.0, v164
	v_add_f32_e32 v165, 1.0, v165
	v_add_f32_e32 v166, 1.0, v166
	v_add_f32_e32 v167, 1.0, v167
	s_waitcnt lgkmcnt(5)
; DI unsigned pk2(float a, float b) { f32x2 v = {a, b}; bf16x2_t r = __builtin_convertvector(v, bf16x2_t); return __builtin_bit_cast(unsigned, r); }
; DI float silu_f(float g) { return g * rcpf_(1.f + ex2(-g * LOG2E)); }
; static __device__ __forceinline__ void phase_ffn_up(const P& p, int l, char* lds) {
;     ...
; #pragma unroll
;           for (int hf = 0; hf < 2; ++hf) {
;             const f32x4 am = *(const f32x4*)(rp - 528 + lca + hf * 16), a0 = *(const f32x4*)(rp + lca + hf * 16), ap = *(const f32x4*)(rp + 528 + lca + hf * 16);
;             const f32x4 gm = *(const f32x4*)(rp - 528 + lcg + hf * 16), g0 = *(const f32x4*)(rp + lcg + hf * 16), gp = *(const f32x4*)(rp + 528 + lcg + hf * 16);
; #pragma unroll
;             for (int e = 0; e < 4; ++e) {
;               const int q = hf * 4 + e;
;               const float ua = wa0[q] * (fm * am[e]) + wa1[q] * a0[e] + wa2[q] * (fp * ap[e]) + ba[q];
;               const float ug = wg0[q] * (fm * gm[e]) + wg1[q] * g0[e] + wg2[q] * (fp * gp[e]) + bg[q];
;               o[q] = silu_f(ug) * ua;
;             }
;           }
;           u32x4 w = {pk2(o[0], o[1]), pk2(o[2], o[3]), pk2(o[4], o[5]), pk2(o[6], o[7])};
;           *(u32x4*)(act + (size_t)tt * DFF + ca0) = w;
	v_pk_fma_f32 v[182:183], v[66:67], v[182:183], v[78:79]
	v_pk_fma_f32 v[184:185], v[68:69], v[184:185], v[80:81]
	s_waitcnt lgkmcnt(4)
	v_pk_fma_f32 v[182:183], v[70:71], v[186:187], v[182:183]
	v_pk_fma_f32 v[184:185], v[72:73], v[188:189], v[184:185]
	s_waitcnt lgkmcnt(3)
	v_pk_fma_f32 v[182:183], v[74:75], v[190:191], v[182:183]
	v_pk_fma_f32 v[184:185], v[76:77], v[192:193], v[184:185]
	v_rcp_f32_e32 v164, v164
	v_rcp_f32_e32 v165, v165
	v_rcp_f32_e32 v166, v166
	v_rcp_f32_e32 v167, v167
	v_pk_mul_f32 v[186:187], v[182:183], s[100:101]
	v_pk_mul_f32 v[188:189], v[184:185], s[100:101]
	v_exp_f32_e32 v186, v186
	v_exp_f32_e32 v187, v187
	v_exp_f32_e32 v188, v188
	v_exp_f32_e32 v189, v189
	s_waitcnt lgkmcnt(2)
	v_pk_fma_f32 v[194:195], v[50:51], v[194:195], v[62:63]
	v_pk_fma_f32 v[196:197], v[52:53], v[196:197], v[64:65]
	s_waitcnt lgkmcnt(1)
	v_pk_fma_f32 v[194:195], v[58:59], v[200:201], v[194:195]
	v_pk_fma_f32 v[196:197], v[60:61], v[202:203], v[196:197]
	s_waitcnt lgkmcnt(0)
	v_pk_fma_f32 v[194:195], v[54:55], v[204:205], v[194:195]
	v_pk_fma_f32 v[196:197], v[56:57], v[206:207], v[196:197]
	v_pk_mul_f32 v[160:161], v[160:161], v[164:165]
	v_pk_mul_f32 v[162:163], v[162:163], v[166:167]
	v_pk_mul_f32 v[160:161], v[172:173], v[160:161]
	v_pk_mul_f32 v[162:163], v[174:175], v[162:163]
	v_cvt_pk_bf16_f32 v114, v160, v161
	v_cvt_pk_bf16_f32 v115, v162, v163
	v_add_f32_e32 v186, 1.0, v186
	v_add_f32_e32 v187, 1.0, v187
	v_add_f32_e32 v188, 1.0, v188
	v_add_f32_e32 v189, 1.0, v189
	v_rcp_f32_e32 v186, v186
	v_rcp_f32_e32 v187, v187
	v_rcp_f32_e32 v188, v188
	v_rcp_f32_e32 v189, v189
	s_movk_i32 s14, 0x1600
	v_mad_i64_i32 v[136:137], s[22:23], v0, s14, v[132:133]
	v_pk_mul_f32 v[182:183], v[182:183], v[186:187]
	v_pk_mul_f32 v[184:185], v[184:185], v[188:189]
	v_pk_mul_f32 v[182:183], v[194:195], v[182:183]
	v_pk_mul_f32 v[184:185], v[196:197], v[184:185]
	v_cvt_pk_bf16_f32 v116, v182, v183
	v_cvt_pk_bf16_f32 v117, v184, v185
	global_store_dwordx4 v[136:137], v[114:117], off
	s_branch .LBB0_1081
.Lcf_2:
	v_mov_b32_e32 v0, v159
	s_mov_b32 s100, 0xbfb8aa3b
	s_mov_b32 s101, 0xbfb8aa3b
	ds_read_b128 v[160:163], v157 offset:1904
	ds_read_b128 v[164:167], v157 offset:2432
	ds_read_b128 v[168:171], v157 offset:2960
	ds_read_b128 v[172:175], v157 offset:1776
	ds_read_b128 v[176:179], v157 offset:2304
	ds_read_b128 v[136:139], v157 offset:2832
	ds_read_b128 v[182:185], v157 offset:1920
	ds_read_b128 v[186:189], v157 offset:2448
	ds_read_b128 v[190:193], v157 offset:2976
	ds_read_b128 v[194:197], v157 offset:1792
	ds_read_b128 v[200:203], v157 offset:2320
	ds_read_b128 v[204:207], v157 offset:2848
	s_waitcnt lgkmcnt(11)
	v_pk_fma_f32 v[160:161], v[98:99], v[160:161], v[110:111]
	v_pk_fma_f32 v[162:163], v[100:101], v[162:163], v[112:113]
	s_waitcnt lgkmcnt(10)
	v_pk_fma_f32 v[160:161], v[102:103], v[164:165], v[160:161]
	v_pk_fma_f32 v[162:163], v[104:105], v[166:167], v[162:163]
	s_waitcnt lgkmcnt(9)
	v_pk_fma_f32 v[160:161], v[106:107], v[168:169], v[160:161]
	v_pk_fma_f32 v[162:163], v[108:109], v[170:171], v[162:163]
	v_pk_mul_f32 v[164:165], v[160:161], s[100:101]
	v_pk_mul_f32 v[166:167], v[162:163], s[100:101]
	v_exp_f32_e32 v164, v164
	v_exp_f32_e32 v165, v165
	v_exp_f32_e32 v166, v166
	v_exp_f32_e32 v167, v167
	s_waitcnt lgkmcnt(8)
	v_pk_fma_f32 v[172:173], v[86:87], v[172:173], v[82:83]
	v_pk_fma_f32 v[174:175], v[88:89], v[174:175], v[84:85]
	s_waitcnt lgkmcnt(7)
	v_pk_fma_f32 v[172:173], v[94:95], v[176:177], v[172:173]
	v_pk_fma_f32 v[174:175], v[96:97], v[178:179], v[174:175]
	s_waitcnt lgkmcnt(6)
	v_pk_fma_f32 v[172:173], v[90:91], v[136:137], v[172:173]
	v_pk_fma_f32 v[174:175], v[92:93], v[138:139], v[174:175]
	v_add_f32_e32 v164, 1.0, v164
	v_add_f32_e32 v165, 1.0, v165
	v_add_f32_e32 v166, 1.0, v166
	v_add_f32_e32 v167, 1.0, v167
	s_waitcnt lgkmcnt(5)
	v_pk_fma_f32 v[182:183], v[66:67], v[182:183], v[78:79]
	v_pk_fma_f32 v[184:185], v[68:69], v[184:185], v[80:81]
	s_waitcnt lgkmcnt(4)
	v_pk_fma_f32 v[182:183], v[70:71], v[186:187], v[182:183]
	v_pk_fma_f32 v[184:185], v[72:73], v[188:189], v[184:185]
	s_waitcnt lgkmcnt(3)
	v_pk_fma_f32 v[182:183], v[74:75], v[190:191], v[182:183]
	v_pk_fma_f32 v[184:185], v[76:77], v[192:193], v[184:185]
	v_rcp_f32_e32 v164, v164
	v_rcp_f32_e32 v165, v165
	v_rcp_f32_e32 v166, v166
	v_rcp_f32_e32 v167, v167
	v_pk_mul_f32 v[186:187], v[182:183], s[100:101]
	v_pk_mul_f32 v[188:189], v[184:185], s[100:101]
	v_exp_f32_e32 v186, v186
	v_exp_f32_e32 v187, v187
	v_exp_f32_e32 v188, v188
	v_exp_f32_e32 v189, v189
	s_waitcnt lgkmcnt(2)
	v_pk_fma_f32 v[194:195], v[50:51], v[194:195], v[62:63]
	v_pk_fma_f32 v[196:197], v[52:53], v[196:197], v[64:65]
	s_waitcnt lgkmcnt(1)
	v_pk_fma_f32 v[194:195], v[58:59], v[200:201], v[194:195]
	v_pk_fma_f32 v[196:197], v[60:61], v[202:203], v[196:197]
	s_waitcnt lgkmcnt(0)
	v_pk_fma_f32 v[194:195], v[54:55], v[204:205], v[194:195]
	v_pk_fma_f32 v[196:197], v[56:57], v[206:207], v[196:197]
	v_pk_mul_f32 v[160:161], v[160:161], v[164:165]
	v_pk_mul_f32 v[162:163], v[162:163], v[166:167]
	v_pk_mul_f32 v[160:161], v[172:173], v[160:161]
	v_pk_mul_f32 v[162:163], v[174:175], v[162:163]
	v_cvt_pk_bf16_f32 v114, v160, v161
	v_cvt_pk_bf16_f32 v115, v162, v163
	v_add_f32_e32 v186, 1.0, v186
	v_add_f32_e32 v187, 1.0, v187
	v_add_f32_e32 v188, 1.0, v188
	v_add_f32_e32 v189, 1.0, v189
	v_rcp_f32_e32 v186, v186
	v_rcp_f32_e32 v187, v187
	v_rcp_f32_e32 v188, v188
	v_rcp_f32_e32 v189, v189
	s_movk_i32 s14, 0x1600
	v_mad_i64_i32 v[136:137], s[22:23], v0, s14, v[132:133]
	v_pk_mul_f32 v[182:183], v[182:183], v[186:187]
	v_pk_mul_f32 v[184:185], v[184:185], v[188:189]
	v_pk_mul_f32 v[182:183], v[194:195], v[182:183]
	v_pk_mul_f32 v[184:185], v[196:197], v[184:185]
	v_cvt_pk_bf16_f32 v116, v182, v183
	v_cvt_pk_bf16_f32 v117, v184, v185
	global_store_dwordx4 v[136:137], v[114:117], off
	s_branch .LBB0_1083
; DI unsigned pk2(float a, float b) { f32x2 v = {a, b}; bf16x2_t r = __builtin_convertvector(v, bf16x2_t); return __builtin_bit_cast(unsigned, r); }
; DI float silu_f(float g) { return g * rcpf_(1.f + ex2(-g * LOG2E)); }
; static __device__ __forceinline__ void phase_ffn_up(const P& p, int l, char* lds) {
;     ...
; #pragma unroll
;           for (int hf = 0; hf < 2; ++hf) {
;             const f32x4 am = *(const f32x4*)(rp - 528 + lca + hf * 16), a0 = *(const f32x4*)(rp + lca + hf * 16), ap = *(const f32x4*)(rp + 528 + lca + hf * 16);
;             const f32x4 gm = *(const f32x4*)(rp - 528 + lcg + hf * 16), g0 = *(const f32x4*)(rp + lcg + hf * 16), gp = *(const f32x4*)(rp + 528 + lcg + hf * 16);
; #pragma unroll
;             for (int e = 0; e < 4; ++e) {
;               const int q = hf * 4 + e;
;               const float ua = wa0[q] * (fm * am[e]) + wa1[q] * a0[e] + wa2[q] * (fp * ap[e]) + ba[q];
;               const float ug = wg0[q] * (fm * gm[e]) + wg1[q] * g0[e] + wg2[q] * (fp * gp[e]) + bg[q];
;               o[q] = silu_f(ug) * ua;
;             }
;           }
;           u32x4 w = {pk2(o[0], o[1]), pk2(o[2], o[3]), pk2(o[4], o[5]), pk2(o[6], o[7])};
;           *(u32x4*)(act + (size_t)tt * DFF + ca0) = w;
.Lcf_3:
	v_mov_b32_e32 v0, v136
	s_mov_b32 s100, 0xbfb8aa3b
	s_mov_b32 s101, 0xbfb8aa3b
	ds_read_b128 v[160:163], v157 offset:35696
	ds_read_b128 v[164:167], v157 offset:36224
	ds_read_b128 v[168:171], v157 offset:36752
	ds_read_b128 v[172:175], v157 offset:35568
	ds_read_b128 v[176:179], v157 offset:36096
	ds_read_b128 v[136:139], v157 offset:36624
	ds_read_b128 v[182:185], v157 offset:35712
	ds_read_b128 v[186:189], v157 offset:36240
	ds_read_b128 v[190:193], v157 offset:36768
	ds_read_b128 v[194:197], v157 offset:35584
	ds_read_b128 v[200:203], v157 offset:36112
	ds_read_b128 v[204:207], v157 offset:36640
	s_waitcnt lgkmcnt(11)
	v_pk_fma_f32 v[160:161], v[98:99], v[160:161], v[110:111]
	v_pk_fma_f32 v[162:163], v[100:101], v[162:163], v[112:113]
	s_waitcnt lgkmcnt(10)
	v_pk_fma_f32 v[160:161], v[102:103], v[164:165], v[160:161]
	v_pk_fma_f32 v[162:163], v[104:105], v[166:167], v[162:163]
	s_waitcnt lgkmcnt(9)
	v_pk_fma_f32 v[160:161], v[106:107], v[168:169], v[160:161]
	v_pk_fma_f32 v[162:163], v[108:109], v[170:171], v[162:163]
	v_pk_mul_f32 v[164:165], v[160:161], s[100:101]
	v_pk_mul_f32 v[166:167], v[162:163], s[100:101]
	v_exp_f32_e32 v164, v164
	v_exp_f32_e32 v165, v165
	v_exp_f32_e32 v166, v166
	v_exp_f32_e32 v167, v167
	s_waitcnt lgkmcnt(8)
	v_pk_fma_f32 v[172:173], v[86:87], v[172:173], v[82:83]
	v_pk_fma_f32 v[174:175], v[88:89], v[174:175], v[84:85]
	s_waitcnt lgkmcnt(7)
	v_pk_fma_f32 v[172:173], v[94:95], v[176:177], v[172:173]
	v_pk_fma_f32 v[174:175], v[96:97], v[178:179], v[174:175]
	s_waitcnt lgkmcnt(6)
	v_pk_fma_f32 v[172:173], v[90:91], v[136:137], v[172:173]
	v_pk_fma_f32 v[174:175], v[92:93], v[138:139], v[174:175]
	v_add_f32_e32 v164, 1.0, v164
	v_add_f32_e32 v165, 1.0, v165
	v_add_f32_e32 v166, 1.0, v166
	v_add_f32_e32 v167, 1.0, v167
	s_waitcnt lgkmcnt(5)
	v_pk_fma_f32 v[182:183], v[66:67], v[182:183], v[78:79]
	v_pk_fma_f32 v[184:185], v[68:69], v[184:185], v[80:81]
	s_waitcnt lgkmcnt(4)
	v_pk_fma_f32 v[182:183], v[70:71], v[186:187], v[182:183]
	v_pk_fma_f32 v[184:185], v[72:73], v[188:189], v[184:185]
	s_waitcnt lgkmcnt(3)
	v_pk_fma_f32 v[182:183], v[74:75], v[190:191], v[182:183]
	v_pk_fma_f32 v[184:185], v[76:77], v[192:193], v[184:185]
	v_rcp_f32_e32 v164, v164
	v_rcp_f32_e32 v165, v165
	v_rcp_f32_e32 v166, v166
	v_rcp_f32_e32 v167, v167
	v_pk_mul_f32 v[186:187], v[182:183], s[100:101]
	v_pk_mul_f32 v[188:189], v[184:185], s[100:101]
	v_exp_f32_e32 v186, v186
	v_exp_f32_e32 v187, v187
	v_exp_f32_e32 v188, v188
	v_exp_f32_e32 v189, v189
	s_waitcnt lgkmcnt(2)
	v_pk_fma_f32 v[194:195], v[50:51], v[194:195], v[62:63]
	v_pk_fma_f32 v[196:197], v[52:53], v[196:197], v[64:65]
	s_waitcnt lgkmcnt(1)
	v_pk_fma_f32 v[194:195], v[58:59], v[200:201], v[194:195]
	v_pk_fma_f32 v[196:197], v[60:61], v[202:203], v[196:197]
	s_waitcnt lgkmcnt(0)
	v_pk_fma_f32 v[194:195], v[54:55], v[204:205], v[194:195]
	v_pk_fma_f32 v[196:197], v[56:57], v[206:207], v[196:197]
	v_pk_mul_f32 v[160:161], v[160:161], v[164:165]
	v_pk_mul_f32 v[162:163], v[162:163], v[166:167]
	v_pk_mul_f32 v[160:161], v[172:173], v[160:161]
	v_pk_mul_f32 v[162:163], v[174:175], v[162:163]
	v_cvt_pk_bf16_f32 v114, v160, v161
	v_cvt_pk_bf16_f32 v115, v162, v163
	v_add_f32_e32 v186, 1.0, v186
	v_add_f32_e32 v187, 1.0, v187
	v_add_f32_e32 v188, 1.0, v188
	v_add_f32_e32 v189, 1.0, v189
	v_rcp_f32_e32 v186, v186
	v_rcp_f32_e32 v187, v187
	v_rcp_f32_e32 v188, v188
	v_rcp_f32_e32 v189, v189
	s_movk_i32 s14, 0x1600
	v_mad_i64_i32 v[136:137], s[22:23], v0, s14, v[132:133]
	v_pk_mul_f32 v[182:183], v[182:183], v[186:187]
	v_pk_mul_f32 v[184:185], v[184:185], v[188:189]
	v_pk_mul_f32 v[182:183], v[194:195], v[182:183]
	v_pk_mul_f32 v[184:185], v[196:197], v[184:185]
	v_cvt_pk_bf16_f32 v116, v182, v183
	v_cvt_pk_bf16_f32 v117, v184, v185
	global_store_dwordx4 v[136:137], v[114:117], off
	s_branch .LBB0_1058

; __global__ void __launch_bounds__(NTHREADS) fwd_kernel(P p) {
	.amdhsa_kernel _Z10fwd_kernel1P
		.amdhsa_group_segment_fixed_size 0
		.amdhsa_private_segment_fixed_size 0
		.amdhsa_kernarg_size 536
		.amdhsa_user_sgpr_count 2
		.amdhsa_user_sgpr_dispatch_ptr 0
		.amdhsa_user_sgpr_queue_ptr 0
		.amdhsa_user_sgpr_kernarg_segment_ptr 1
		.amdhsa_user_sgpr_dispatch_id 0
		.amdhsa_user_sgpr_kernarg_preload_length 0
		.amdhsa_user_sgpr_kernarg_preload_offset 0
		.amdhsa_user_sgpr_private_segment_size 0
		.amdhsa_uses_dynamic_stack 0
		.amdhsa_enable_private_segment 0
		.amdhsa_system_sgpr_workgroup_id_x 1
		.amdhsa_system_sgpr_workgroup_id_y 0
		.amdhsa_system_sgpr_workgroup_id_z 0
		.amdhsa_system_sgpr_workgroup_info 0
		.amdhsa_system_vgpr_workitem_id 2
		.amdhsa_next_free_vgpr 256
		.amdhsa_next_free_sgpr 102
		.amdhsa_accum_offset 256
		.amdhsa_reserve_vcc 1
		.amdhsa_float_round_mode_32 0
		.amdhsa_float_round_mode_16_64 0
		.amdhsa_float_denorm_mode_32 3
		.amdhsa_float_denorm_mode_16_64 3
		.amdhsa_dx10_clamp 1
		.amdhsa_ieee_mode 1
		.amdhsa_fp16_overflow 0
		.amdhsa_tg_split 0
		.amdhsa_exception_fp_ieee_invalid_op 0
		.amdhsa_exception_fp_denorm_src 0
		.amdhsa_exception_fp_ieee_div_zero 0
		.amdhsa_exception_fp_ieee_overflow 0
		.amdhsa_exception_fp_ieee_underflow 0
		.amdhsa_exception_fp_ieee_inexact 0
		.amdhsa_exception_int_div_zero 0
	.end_amdhsa_kernel

; __global__ void __launch_bounds__(NTHREADS) fwd_kernel(P p) {
amdhsa.kernels:
  - .agpr_count:     0
    .args:
      - .offset:         0
        .size:           280
        .value_kind:     by_value
      - .offset:         280
        .size:           4
        .value_kind:     hidden_block_count_x
      - .offset:         284
        .size:           4
        .value_kind:     hidden_block_count_y
      - .offset:         288
        .size:           4
        .value_kind:     hidden_block_count_z
      - .offset:         292
        .size:           2
        .value_kind:     hidden_group_size_x
      - .offset:         294
        .size:           2
        .value_kind:     hidden_group_size_y
      - .offset:         296
        .size:           2
        .value_kind:     hidden_group_size_z
      - .offset:         298
        .size:           2
        .value_kind:     hidden_remainder_x
      - .offset:         300
        .size:           2
        .value_kind:     hidden_remainder_y
      - .offset:         302
        .size:           2
        .value_kind:     hidden_remainder_z
      - .offset:         320
        .size:           8
        .value_kind:     hidden_global_offset_x
      - .offset:         328
        .size:           8
        .value_kind:     hidden_global_offset_y
      - .offset:         336
        .size:           8
        .value_kind:     hidden_global_offset_z
      - .offset:         344
        .size:           2
        .value_kind:     hidden_grid_dims
      - .offset:         368
        .size:           8
        .value_kind:     hidden_multigrid_sync_arg
      - .offset:         400
        .size:           4
        .value_kind:     hidden_dynamic_lds_size
    .group_segment_fixed_size: 0
    .kernarg_segment_align: 8
    .kernarg_segment_size: 536
    .language:       OpenCL C
    .language_version:
      - 2
      - 0
    .max_flat_workgroup_size: 512
    .name:           _Z10fwd_kernel1P
    .private_segment_fixed_size: 0
    .sgpr_count:     108
    .sgpr_spill_count: 229
    .symbol:         _Z10fwd_kernel1P.kd
    .uniform_work_group_size: 1
    .uses_dynamic_stack: false
    .vgpr_count:     256
    .vgpr_spill_count: 0
    .wavefront_size: 64
